# gather split-tail token staggered: blocks <256 after main token 8, blocks >=256 after main token 4
# speedup vs baseline: 1.0044x; 1.0044x over previous
.LBB0_324:
	s_nop 0
	v_readlane_b32 s0, v249, 46
	v_readlane_b32 s1, v249, 47
	s_and_b64 vcc, exec, s[0:1]
	s_cbranch_vccz .LBB0_345
	v_mov_b32_e32 v1, v220
	v_readlane_b32 s0, v249, 0
	s_nop 0
	v_ashrrev_i32_e32 v0, 6, v1
	v_lshl_add_u32 v116, s0, 2, v0
	v_readfirstlane_b32 s60, v0
	v_readlane_b32 s55, v249, 9
	s_mov_b32 s54, 0
	s_movk_i32 s56, 0x4200
	s_mov_b32 s58, 0
	s_mov_b32 s59, 0
	s_movk_i32 s61, 0xe00
	s_cmp_eq_u32 s55, 0x800
	s_cselect_b32 s55, 1, 0
	s_cselect_b32 s56, 0x4000, s56
	s_sub_u32 s57, s56, 1
	s_lshl_b32 s62, s60, 13
	s_or_b32 s62, s62, 0x8000
	v_readlane_b32 s63, v249, 0
	s_mov_b32 s45, 0
	s_bitcmp1_b32 s63, 8
	s_cselect_b32 s32, 4, 8
	s_lshr_b32 s63, s63, 7
	s_and_b32 s63, s63, 2
	v_cmp_gt_i32_e32 vcc, s56, v116
	s_and_saveexec_b64 s[0:1], vcc
	s_cbranch_execz .LBB0_344
	v_readlane_b32 s2, v249, 37
	v_readlane_b32 s26, v249, 30
	v_readlane_b32 s3, v249, 38
	v_readlane_b32 s27, v249, 31
	s_mul_hi_i32 s4, s2, 0x1400000
	s_mul_i32 s5, s2, 0x1400000
	s_load_dwordx2 s[2:3], s[26:27], 0x160
	v_and_b32_e32 v6, 31, v1
	v_mul_u32_u24_e32 v2, 24, v6
	v_mov_b32_e32 v3, v80
	v_and_b32_e32 v81, 63, v1
	v_and_b32_e32 v255, 32, v81
	v_lshlrev_b32_e32 v255, 2, v255
	s_waitcnt lgkmcnt(0)
	s_add_u32 s2, s2, s5
	s_addc_u32 s3, s3, s4
	v_lshl_add_u64 v[118:119], s[2:3], 0, v[2:3]
	v_lshlrev_b32_e32 v2, 4, v6
	s_getpc_b64 s[4:5]
	s_add_u32 s4, s4, c_cand@rel32@lo+4
	s_addc_u32 s5, s5, c_cand@rel32@hi+12
	v_lshl_add_u64 v[120:121], s[2:3], 0, v[2:3]
	s_load_dwordx4 s[12:15], s[26:27], 0x90
	s_load_dwordx2 s[2:3], s[26:27], 0xc8
	global_load_ubyte v2, v81, s[4:5]
	v_readlane_b32 s16, v249, 13
	s_sub_i32 s10, s16, 19
	s_cmp_lt_u32 s10, 6
	s_cselect_b64 s[4:5], -1, 0
	s_cmp_gt_u32 s10, 5
	v_readlane_b32 s10, v249, 39
	v_readlane_b32 s11, v249, 40
	s_cselect_b64 s[20:21], -1, 0
	s_lshl_b64 s[10:11], s[10:11], 2
	s_waitcnt lgkmcnt(0)
	s_add_u32 s22, s14, s10
	s_addc_u32 s23, s15, s11
	s_add_u32 s24, s12, s10
	s_addc_u32 s25, s13, s11
	s_load_dwordx2 s[10:11], s[26:27], 0x140
	v_lshlrev_b32_e32 v3, 3, v81
	v_lshlrev_b32_e32 v4, 6, v6
	v_mov_b32_e32 v5, v80
	v_lshl_or_b32 v239, v0, 12, v3
	s_waitcnt lgkmcnt(0)
	v_lshl_add_u64 v[122:123], s[10:11], 0, v[4:5]
	v_and_b32_e32 v3, 3, v1
	v_and_b32_e32 v4, 64, v229
	v_cmp_eq_u32_e64 s[12:13], 0, v3
	v_xor_b32_e32 v3, 4, v229
	v_add_u32_e32 v4, 64, v4
	v_cmp_lt_i32_e32 vcc, v3, v4
	v_readlane_b32 s18, v249, 15
	v_readlane_b32 s19, v249, 16
	v_cndmask_b32_e32 v3, v229, v3, vcc
	v_lshlrev_b32_e32 v240, 2, v3
	v_xor_b32_e32 v3, 8, v229
	v_cmp_lt_i32_e32 vcc, v3, v4
	v_readlane_b32 s17, v249, 14
	v_cmp_lt_u32_e64 s[6:7], 31, v81
	v_cndmask_b32_e32 v3, v229, v3, vcc
	v_lshlrev_b32_e32 v241, 2, v3
	v_xor_b32_e32 v3, 16, v229
	v_cmp_lt_i32_e32 vcc, v3, v4
	v_cmp_gt_u32_e64 s[8:9], 32, v81
	v_cmp_gt_u32_e64 s[10:11], 50, v81
	v_cndmask_b32_e32 v3, v229, v3, vcc
	v_lshlrev_b32_e32 v242, 2, v3
	v_xor_b32_e32 v3, 32, v229
	v_cmp_lt_i32_e32 vcc, v3, v4
	s_waitcnt vmcnt(0)
	v_and_b32_e32 v0, 15, v2
	v_cndmask_b32_e32 v3, v229, v3, vcc
	v_lshlrev_b32_e32 v243, 2, v3
	v_and_b32_e32 v3, 16, v1
	v_cmp_eq_u32_e64 s[14:15], 0, v3
	v_and_b32_e32 v3, 8, v1
	v_and_b32_e32 v1, 4, v1
	v_cmp_eq_u32_e64 s[18:19], 0, v1
	v_xor_b32_e32 v1, 2, v229
	v_cmp_lt_i32_e32 vcc, v1, v4
	v_lshrrev_b32_e32 v2, 4, v2
	v_cmp_eq_u32_e64 s[16:17], 0, v3
	v_cndmask_b32_e32 v1, v229, v1, vcc
	v_lshlrev_b32_e32 v244, 2, v1
	v_xor_b32_e32 v1, 1, v229
	v_cmp_lt_i32_e32 vcc, v1, v4
	v_lshlrev_b32_e32 v4, 7, v6
	v_lshl_add_u64 v[124:125], s[24:25], 0, v[4:5]
	v_cndmask_b32_e32 v1, v229, v1, vcc
	v_lshlrev_b32_e32 v245, 2, v1
	v_lshl_add_u64 v[126:127], s[22:23], 0, v[4:5]
	v_lshl_add_u64 v[128:129], s[2:3], 0, v[4:5]
	s_mov_b64 s[22:23], 0
	v_lshlrev_b32_e32 v130, 2, v2
	v_lshlrev_b32_e32 v132, 2, v0
	s_branch .LBB0_328
.LBB0_327:
	s_or_b64 exec, exec, s[2:3]
	s_cmp_eq_u32 s55, 0
	s_cbranch_scc1 .Lg_latch
	s_cmp_eq_u32 s54, 1
	s_cbranch_scc1 .Lg_tail_end
	s_add_u32 s45, s45, 1
	s_cmp_lg_u32 s45, s32
	s_cbranch_scc1 .Lg_latch
	s_mov_b32 s54, 1
	v_readfirstlane_b32 s47, v116
	s_lshl_b32 s58, s60, 8
	s_movk_i32 s61, 0x200
	v_readlane_b32 s2, v249, 0
	s_add_u32 s2, s2, 0x4000
	v_mov_b32_e32 v116, s2
	s_branch .LBB0_328
.Lg_tail_end:
	s_mov_b32 s54, 0
	s_mov_b32 s32, -1
	s_mov_b32 s58, 0
	s_movk_i32 s61, 0xe00
	v_mov_b32_e32 v116, s47
.Lg_latch:
	v_readlane_b32 s2, v249, 9
	s_nop 1
	v_add_u32_e32 v116, s2, v116
	v_cmp_lt_i32_e32 vcc, s57, v116
	s_or_b64 s[22:23], vcc, s[22:23]
	s_andn2_b64 exec, exec, s[22:23]
	s_cbranch_execz .LBB0_344
